# XB2: grid barrier direct completion wait - every workgroup polls the top-level count >= (gen+1)*nx; no generation words
# baseline (speedup 1.0000x reference)
; __device__ __forceinline__ unsigned xb_ld(unsigned* p)              { return __hip_atomic_load(p, __ATOMIC_RELAXED, __HIP_MEMORY_SCOPE_AGENT); }
; __device__ __forceinline__ unsigned xb_add(unsigned* p, unsigned v) { return __hip_atomic_fetch_add(p, v, __ATOMIC_RELAXED, __HIP_MEMORY_SCOPE_AGENT); }
; #define XB_SPIN(cond, bar) do { unsigned _sp = 0; while (cond) { __builtin_amdgcn_s_sleep(1); \
;     if ((++_sp & 255u) == 0u) { if (xb_ld(&(bar)[XB_TMO])) break; if (_sp > XB_SPIN_CAP) { atomicAdd(&(bar)[XB_TMO], 1u); break; } } } } while (0)
; __device__ __forceinline__ void xcd_barrier(const XcdBarrier& b) {
;     ...
;         const unsigned old = xb_add(&bar[XB_XSUB(b.x)], 1u);
;         const unsigned gen = old / nloc;
;         if (old + 1u == (gen + 1u) * nloc) {
;             __builtin_amdgcn_fence(__ATOMIC_RELEASE, "agent");
;             asm volatile("s_waitcnt vmcnt(0)" ::: "memory");
;             const unsigned og = xb_add(&bar[XB_TOP], 1u);
;             const unsigned tg = og / nx;
;             if (og + 1u == (tg + 1u) * nx) xb_add(&bar[XB_TOPGEN], 1u);
;             else XB_SPIN(xb_ld(&bar[XB_TOPGEN]) == tg, bar);
;             __builtin_amdgcn_fence(__ATOMIC_ACQUIRE, "agent");
;             xb_add(&bar[XB_XGEN(b.x)], 1u);
;             asm volatile("s_waitcnt vmcnt(0)" ::: "memory");
;         } else {
;             XB_SPIN(xb_ld(&bar[XB_XGEN(b.x)]) == gen, bar);
;             __builtin_amdgcn_fence(__ATOMIC_ACQUIRE, "agent");
;             asm volatile("s_waitcnt vmcnt(0)" ::: "memory");
.LBB0_412:
	s_or_b64 exec, exec, s[8:9]
	v_cvt_f32_u32_e32 v7, v5
	s_waitcnt vmcnt(0)
	v_readfirstlane_b32 s6, v6
	v_sub_u32_e32 v6, 0, v5
	v_rcp_iflag_f32_e32 v7, v7
	v_add_u32_e32 v8, s6, v2
	v_mul_f32_e32 v7, 0x4f7ffffe, v7
	v_cvt_u32_f32_e32 v7, v7
	v_mul_lo_u32 v2, v6, v7
	v_mul_hi_u32 v2, v7, v2
	v_add_u32_e32 v2, v7, v2
	v_mul_hi_u32 v2, v8, v2
	v_mul_lo_u32 v6, v2, v5
	v_sub_u32_e32 v6, v8, v6
	v_add_u32_e32 v7, 1, v2
	v_cmp_ge_u32_e32 vcc, v6, v5
	s_nop 1
	v_cndmask_b32_e32 v2, v2, v7, vcc
	v_sub_u32_e32 v7, v6, v5
	v_cndmask_b32_e32 v6, v6, v7, vcc
	v_add_u32_e32 v7, 1, v2
	v_cmp_ge_u32_e32 vcc, v6, v5
	v_add_u32_e32 v6, 1, v8
	s_nop 0
	v_cndmask_b32_e32 v2, v2, v7, vcc
	v_mul_lo_u32 v7, v5, v2
	v_add_u32_e32 v5, v7, v5
	v_cmp_ne_u32_e32 vcc, v6, v5
	s_waitcnt lgkmcnt(0)
	v_mad_u32_u24 v19, v2, v4, v4
	s_add_u32 s100, s4, 0x83400
	s_addc_u32 s101, s5, 0
	s_and_saveexec_b64 s[6:7], vcc
	s_xor_b64 s[6:7], exec, s[6:7]
	s_cbranch_execz .LBB0_426
	s_add_i32 s30, s40, 0x900
	s_lshl_b64 s[8:9], s[30:31], 2
	s_add_u32 s46, s34, s8
	s_addc_u32 s47, s35, s9
	s_waitcnt lgkmcnt(0)
	global_load_dword v4, v3, s[100:101] sc1
	s_waitcnt vmcnt(0)
	v_cmp_lt_u32_e32 vcc, v4, v19
	s_and_saveexec_b64 s[8:9], vcc
	s_cbranch_execz .LBB0_425
	s_add_u32 s14, s4, 0x80200
	s_addc_u32 s15, s5, 0
	s_mov_b32 s30, 1
	s_mov_b64 s[52:53], 0
	s_branch .LBB0_416

; __device__ __forceinline__ unsigned xb_ld(unsigned* p)              { return __hip_atomic_load(p, __ATOMIC_RELAXED, __HIP_MEMORY_SCOPE_AGENT); }
; #define XB_SPIN(cond, bar) do { unsigned _sp = 0; while (cond) { __builtin_amdgcn_s_sleep(1); \
;     if ((++_sp & 255u) == 0u) { if (xb_ld(&(bar)[XB_TMO])) break; if (_sp > XB_SPIN_CAP) { atomicAdd(&(bar)[XB_TMO], 1u); break; } } } } while (0)
; __device__ __forceinline__ void xcd_barrier(const XcdBarrier& b) {
;     ...
;             XB_SPIN(xb_ld(&bar[XB_XGEN(b.x)]) == gen, bar);
.LBB0_420:
	global_load_dword v4, v3, s[100:101] sc1
	s_add_i32 s30, s30, 1
	s_mov_b64 s[22:23], -1
	s_waitcnt vmcnt(0)
	v_cmp_ge_u32_e32 vcc, v4, v19
	s_orn2_b64 s[16:17], vcc, exec
	s_branch .LBB0_415

; __device__ __forceinline__ unsigned xb_ld(unsigned* p)              { return __hip_atomic_load(p, __ATOMIC_RELAXED, __HIP_MEMORY_SCOPE_AGENT); }
; __device__ __forceinline__ unsigned xb_add(unsigned* p, unsigned v) { return __hip_atomic_fetch_add(p, v, __ATOMIC_RELAXED, __HIP_MEMORY_SCOPE_AGENT); }
; #define XB_SPIN(cond, bar) do { unsigned _sp = 0; while (cond) { __builtin_amdgcn_s_sleep(1); \
;     if ((++_sp & 255u) == 0u) { if (xb_ld(&(bar)[XB_TMO])) break; if (_sp > XB_SPIN_CAP) { atomicAdd(&(bar)[XB_TMO], 1u); break; } } } } while (0)
; __device__ __forceinline__ void xcd_barrier(const XcdBarrier& b) {
;     ...
;         if (old + 1u == (gen + 1u) * nloc) {
;             __builtin_amdgcn_fence(__ATOMIC_RELEASE, "agent");
;             asm volatile("s_waitcnt vmcnt(0)" ::: "memory");
;             const unsigned og = xb_add(&bar[XB_TOP], 1u);
;             const unsigned tg = og / nx;
;             if (og + 1u == (tg + 1u) * nx) xb_add(&bar[XB_TOPGEN], 1u);
;             else XB_SPIN(xb_ld(&bar[XB_TOPGEN]) == tg, bar);
;             __builtin_amdgcn_fence(__ATOMIC_ACQUIRE, "agent");
;             xb_add(&bar[XB_XGEN(b.x)], 1u);
.LBB0_429:
	s_or_b64 exec, exec, s[8:9]
	s_waitcnt vmcnt(0)
	v_readfirstlane_b32 s6, v5
	v_sub_u32_e32 v6, 0, v4
	s_mov_b64 s[14:15], -1
	v_add_u32_e32 v5, s6, v2
	v_cvt_f32_u32_e32 v2, v4
	s_add_u32 s6, s4, 0x83500
	s_addc_u32 s7, s5, 0
	v_rcp_iflag_f32_e32 v2, v2
	s_nop 0
	v_mul_f32_e32 v2, 0x4f7ffffe, v2
	v_cvt_u32_f32_e32 v2, v2
	v_mul_lo_u32 v6, v6, v2
	v_mul_hi_u32 v6, v2, v6
	v_add_u32_e32 v2, v2, v6
	v_mul_hi_u32 v2, v5, v2
	v_mul_lo_u32 v6, v2, v4
	v_sub_u32_e32 v6, v5, v6
	v_cmp_ge_u32_e32 vcc, v6, v4
	v_add_u32_e32 v7, 1, v2
	v_add_u32_e32 v5, 1, v5
	v_cndmask_b32_e32 v2, v2, v7, vcc
	v_sub_u32_e32 v7, v6, v4
	v_cndmask_b32_e32 v6, v6, v7, vcc
	v_cmp_ge_u32_e32 vcc, v6, v4
	v_add_u32_e32 v6, 1, v2
	s_nop 0
	v_cndmask_b32_e32 v2, v2, v6, vcc
	v_mul_lo_u32 v6, v4, v2
	v_add_u32_e32 v4, v6, v4
	v_cmp_ne_u32_e32 vcc, v5, v4
	v_mov_b64_e32 v[4:5], s[6:7]
	s_and_saveexec_b64 s[8:9], vcc
	s_cbranch_execz .LBB0_441
	global_load_dword v4, v3, s[100:101] sc1
	s_mov_b64 s[16:17], 0
	s_waitcnt vmcnt(0)
	v_cmp_lt_u32_e32 vcc, v4, v19
	s_and_saveexec_b64 s[46:47], vcc
	s_cbranch_execz .LBB0_440
	s_add_u32 s14, s4, 0x80200
	s_addc_u32 s15, s5, 0
	s_mov_b32 s30, 1
	s_mov_b64 s[4:5], 0
	s_branch .LBB0_433

; __device__ __forceinline__ unsigned xb_ld(unsigned* p)              { return __hip_atomic_load(p, __ATOMIC_RELAXED, __HIP_MEMORY_SCOPE_AGENT); }
; __device__ __forceinline__ unsigned xb_add(unsigned* p, unsigned v) { return __hip_atomic_fetch_add(p, v, __ATOMIC_RELAXED, __HIP_MEMORY_SCOPE_AGENT); }
; #define XB_SPIN(cond, bar) do { unsigned _sp = 0; while (cond) { __builtin_amdgcn_s_sleep(1); \
;     if ((++_sp & 255u) == 0u) { if (xb_ld(&(bar)[XB_TMO])) break; if (_sp > XB_SPIN_CAP) { atomicAdd(&(bar)[XB_TMO], 1u); break; } } } } while (0)
; __device__ __forceinline__ void xcd_barrier(const XcdBarrier& b) {
;     ...
;         const unsigned old = xb_add(&bar[XB_XSUB(b.x)], 1u);
;         const unsigned gen = old / nloc;
;         if (old + 1u == (gen + 1u) * nloc) {
;             __builtin_amdgcn_fence(__ATOMIC_RELEASE, "agent");
;             asm volatile("s_waitcnt vmcnt(0)" ::: "memory");
;             const unsigned og = xb_add(&bar[XB_TOP], 1u);
;             const unsigned tg = og / nx;
;             if (og + 1u == (tg + 1u) * nx) xb_add(&bar[XB_TOPGEN], 1u);
;             else XB_SPIN(xb_ld(&bar[XB_TOPGEN]) == tg, bar);
;             __builtin_amdgcn_fence(__ATOMIC_ACQUIRE, "agent");
;             xb_add(&bar[XB_XGEN(b.x)], 1u);
;             asm volatile("s_waitcnt vmcnt(0)" ::: "memory");
;         } else {
;             XB_SPIN(xb_ld(&bar[XB_XGEN(b.x)]) == gen, bar);
;             __builtin_amdgcn_fence(__ATOMIC_ACQUIRE, "agent");
;             asm volatile("s_waitcnt vmcnt(0)" ::: "memory");
.LBB0_654:
	s_or_b64 exec, exec, s[6:7]
	v_cvt_f32_u32_e32 v7, v5
	s_waitcnt vmcnt(0)
	v_readfirstlane_b32 s4, v6
	v_sub_u32_e32 v6, 0, v5
	v_rcp_iflag_f32_e32 v7, v7
	v_add_u32_e32 v8, s4, v2
	v_mul_f32_e32 v7, 0x4f7ffffe, v7
	v_cvt_u32_f32_e32 v7, v7
	v_mul_lo_u32 v2, v6, v7
	v_mul_hi_u32 v2, v7, v2
	v_add_u32_e32 v2, v7, v2
	v_mul_hi_u32 v2, v8, v2
	v_mul_lo_u32 v6, v2, v5
	v_sub_u32_e32 v6, v8, v6
	v_add_u32_e32 v7, 1, v2
	v_cmp_ge_u32_e32 vcc, v6, v5
	s_nop 1
	v_cndmask_b32_e32 v2, v2, v7, vcc
	v_sub_u32_e32 v7, v6, v5
	v_cndmask_b32_e32 v6, v6, v7, vcc
	v_add_u32_e32 v7, 1, v2
	v_cmp_ge_u32_e32 vcc, v6, v5
	v_add_u32_e32 v6, 1, v8
	s_nop 0
	v_cndmask_b32_e32 v2, v2, v7, vcc
	v_mul_lo_u32 v7, v5, v2
	v_add_u32_e32 v5, v7, v5
	v_cmp_ne_u32_e32 vcc, v6, v5
	s_waitcnt lgkmcnt(0)
	v_mad_u32_u24 v19, v2, v4, v4
	s_add_u32 s100, s2, 0x83400
	s_addc_u32 s101, s3, 0
	s_and_saveexec_b64 s[4:5], vcc
	s_xor_b64 s[4:5], exec, s[4:5]
	s_cbranch_execz .LBB0_668
	s_add_i32 s30, s40, 0x900
	s_lshl_b64 s[6:7], s[30:31], 2
	s_add_u32 s14, s34, s6
	s_addc_u32 s15, s35, s7
	s_waitcnt lgkmcnt(0)
	global_load_dword v4, v3, s[100:101] sc1
	s_waitcnt vmcnt(0)
	v_cmp_lt_u32_e32 vcc, v4, v19
	s_and_saveexec_b64 s[6:7], vcc
	s_cbranch_execz .LBB0_667
	s_add_u32 s8, s2, 0x80200
	s_addc_u32 s9, s3, 0
	s_mov_b32 s30, 1
	s_mov_b64 s[46:47], 0
	s_branch .LBB0_658

; __device__ __forceinline__ unsigned xb_ld(unsigned* p)              { return __hip_atomic_load(p, __ATOMIC_RELAXED, __HIP_MEMORY_SCOPE_AGENT); }
; __device__ __forceinline__ unsigned xb_add(unsigned* p, unsigned v) { return __hip_atomic_fetch_add(p, v, __ATOMIC_RELAXED, __HIP_MEMORY_SCOPE_AGENT); }
; #define XB_SPIN(cond, bar) do { unsigned _sp = 0; while (cond) { __builtin_amdgcn_s_sleep(1); \
;     if ((++_sp & 255u) == 0u) { if (xb_ld(&(bar)[XB_TMO])) break; if (_sp > XB_SPIN_CAP) { atomicAdd(&(bar)[XB_TMO], 1u); break; } } } } while (0)
; __device__ __forceinline__ void xcd_barrier(const XcdBarrier& b) {
;     ...
;         if (old + 1u == (gen + 1u) * nloc) {
;             __builtin_amdgcn_fence(__ATOMIC_RELEASE, "agent");
;             asm volatile("s_waitcnt vmcnt(0)" ::: "memory");
;             const unsigned og = xb_add(&bar[XB_TOP], 1u);
;             const unsigned tg = og / nx;
;             if (og + 1u == (tg + 1u) * nx) xb_add(&bar[XB_TOPGEN], 1u);
;             else XB_SPIN(xb_ld(&bar[XB_TOPGEN]) == tg, bar);
;             __builtin_amdgcn_fence(__ATOMIC_ACQUIRE, "agent");
;             xb_add(&bar[XB_XGEN(b.x)], 1u);
.LBB0_671:
	s_or_b64 exec, exec, s[6:7]
	s_waitcnt vmcnt(0)
	v_readfirstlane_b32 s4, v5
	v_sub_u32_e32 v6, 0, v4
	s_mov_b64 s[8:9], -1
	v_add_u32_e32 v5, s4, v2
	v_cvt_f32_u32_e32 v2, v4
	s_add_u32 s4, s2, 0x83500
	s_addc_u32 s5, s3, 0
	v_rcp_iflag_f32_e32 v2, v2
	s_nop 0
	v_mul_f32_e32 v2, 0x4f7ffffe, v2
	v_cvt_u32_f32_e32 v2, v2
	v_mul_lo_u32 v6, v6, v2
	v_mul_hi_u32 v6, v2, v6
	v_add_u32_e32 v2, v2, v6
	v_mul_hi_u32 v2, v5, v2
	v_mul_lo_u32 v6, v2, v4
	v_sub_u32_e32 v6, v5, v6
	v_cmp_ge_u32_e32 vcc, v6, v4
	v_add_u32_e32 v7, 1, v2
	v_add_u32_e32 v5, 1, v5
	v_cndmask_b32_e32 v2, v2, v7, vcc
	v_sub_u32_e32 v7, v6, v4
	v_cndmask_b32_e32 v6, v6, v7, vcc
	v_cmp_ge_u32_e32 vcc, v6, v4
	v_add_u32_e32 v6, 1, v2
	s_nop 0
	v_cndmask_b32_e32 v2, v2, v6, vcc
	v_mul_lo_u32 v6, v4, v2
	v_add_u32_e32 v4, v6, v4
	v_cmp_ne_u32_e32 vcc, v5, v4
	v_mov_b64_e32 v[4:5], s[4:5]
	s_and_saveexec_b64 s[6:7], vcc
	s_cbranch_execz .LBB0_683
	global_load_dword v4, v3, s[100:101] sc1
	s_mov_b64 s[16:17], 0
	s_waitcnt vmcnt(0)
	v_cmp_lt_u32_e32 vcc, v4, v19
	s_and_saveexec_b64 s[14:15], vcc
	s_cbranch_execz .LBB0_682
	s_add_u32 s8, s2, 0x80200
	s_addc_u32 s9, s3, 0
	s_mov_b32 s30, 1
	s_mov_b64 s[2:3], 0
	s_branch .LBB0_675

; __device__ __forceinline__ unsigned xb_ld(unsigned* p)              { return __hip_atomic_load(p, __ATOMIC_RELAXED, __HIP_MEMORY_SCOPE_AGENT); }
; __device__ __forceinline__ unsigned xb_add(unsigned* p, unsigned v) { return __hip_atomic_fetch_add(p, v, __ATOMIC_RELAXED, __HIP_MEMORY_SCOPE_AGENT); }
; #define XB_SPIN(cond, bar) do { unsigned _sp = 0; while (cond) { __builtin_amdgcn_s_sleep(1); \
;     if ((++_sp & 255u) == 0u) { if (xb_ld(&(bar)[XB_TMO])) break; if (_sp > XB_SPIN_CAP) { atomicAdd(&(bar)[XB_TMO], 1u); break; } } } } while (0)
; __device__ __forceinline__ void xcd_barrier(const XcdBarrier& b) {
;     ...
;         const unsigned old = xb_add(&bar[XB_XSUB(b.x)], 1u);
;         const unsigned gen = old / nloc;
;         if (old + 1u == (gen + 1u) * nloc) {
;             __builtin_amdgcn_fence(__ATOMIC_RELEASE, "agent");
;             asm volatile("s_waitcnt vmcnt(0)" ::: "memory");
;             const unsigned og = xb_add(&bar[XB_TOP], 1u);
;             const unsigned tg = og / nx;
;             if (og + 1u == (tg + 1u) * nx) xb_add(&bar[XB_TOPGEN], 1u);
;             else XB_SPIN(xb_ld(&bar[XB_TOPGEN]) == tg, bar);
;             __builtin_amdgcn_fence(__ATOMIC_ACQUIRE, "agent");
;             xb_add(&bar[XB_XGEN(b.x)], 1u);
;             asm volatile("s_waitcnt vmcnt(0)" ::: "memory");
;         } else {
;             XB_SPIN(xb_ld(&bar[XB_XGEN(b.x)]) == gen, bar);
;             __builtin_amdgcn_fence(__ATOMIC_ACQUIRE, "agent");
;             asm volatile("s_waitcnt vmcnt(0)" ::: "memory");
.LBB0_906:
	s_or_b64 exec, exec, s[6:7]
	v_cvt_f32_u32_e32 v7, v5
	s_waitcnt vmcnt(0)
	v_readfirstlane_b32 s4, v6
	v_sub_u32_e32 v6, 0, v5
	v_rcp_iflag_f32_e32 v7, v7
	v_add_u32_e32 v8, s4, v2
	v_mul_f32_e32 v7, 0x4f7ffffe, v7
	v_cvt_u32_f32_e32 v7, v7
	v_mul_lo_u32 v2, v6, v7
	v_mul_hi_u32 v2, v7, v2
	v_add_u32_e32 v2, v7, v2
	v_mul_hi_u32 v2, v8, v2
	v_mul_lo_u32 v6, v2, v5
	v_sub_u32_e32 v6, v8, v6
	v_add_u32_e32 v7, 1, v2
	v_cmp_ge_u32_e32 vcc, v6, v5
	s_nop 1
	v_cndmask_b32_e32 v2, v2, v7, vcc
	v_sub_u32_e32 v7, v6, v5
	v_cndmask_b32_e32 v6, v6, v7, vcc
	v_add_u32_e32 v7, 1, v2
	v_cmp_ge_u32_e32 vcc, v6, v5
	v_add_u32_e32 v6, 1, v8
	s_nop 0
	v_cndmask_b32_e32 v2, v2, v7, vcc
	v_mul_lo_u32 v7, v5, v2
	v_add_u32_e32 v5, v7, v5
	v_cmp_ne_u32_e32 vcc, v6, v5
	s_waitcnt lgkmcnt(0)
	v_mad_u32_u24 v19, v2, v4, v4
	s_add_u32 s100, s2, 0x83400
	s_addc_u32 s101, s3, 0
	s_and_saveexec_b64 s[4:5], vcc
	s_xor_b64 s[4:5], exec, s[4:5]
	s_cbranch_execz .LBB0_920
	s_add_i32 s6, s40, 0x900
	s_mov_b32 s7, s31
	s_lshl_b64 s[6:7], s[6:7], 2
	s_add_u32 s14, s34, s6
	s_addc_u32 s15, s35, s7
	s_waitcnt lgkmcnt(0)
	global_load_dword v4, v3, s[100:101] sc1
	s_waitcnt vmcnt(0)
	v_cmp_lt_u32_e32 vcc, v4, v19
	s_and_saveexec_b64 s[6:7], vcc
	s_cbranch_execz .LBB0_919
	s_add_u32 s8, s2, 0x80200
	s_addc_u32 s9, s3, 0
	s_mov_b32 s41, 1
	s_mov_b64 s[46:47], 0
	s_branch .LBB0_910

; __device__ __forceinline__ unsigned xb_ld(unsigned* p)              { return __hip_atomic_load(p, __ATOMIC_RELAXED, __HIP_MEMORY_SCOPE_AGENT); }
; #define XB_SPIN(cond, bar) do { unsigned _sp = 0; while (cond) { __builtin_amdgcn_s_sleep(1); \
;     if ((++_sp & 255u) == 0u) { if (xb_ld(&(bar)[XB_TMO])) break; if (_sp > XB_SPIN_CAP) { atomicAdd(&(bar)[XB_TMO], 1u); break; } } } } while (0)
; __device__ __forceinline__ void xcd_barrier(const XcdBarrier& b) {
;     ...
;             XB_SPIN(xb_ld(&bar[XB_XGEN(b.x)]) == gen, bar);
.LBB0_914:
	global_load_dword v4, v3, s[100:101] sc1
	s_add_i32 s41, s41, 1
	s_mov_b64 s[22:23], -1
	s_waitcnt vmcnt(0)
	v_cmp_ge_u32_e32 vcc, v4, v19
	s_orn2_b64 s[16:17], vcc, exec
	s_branch .LBB0_909

; __device__ __forceinline__ unsigned xb_ld(unsigned* p)              { return __hip_atomic_load(p, __ATOMIC_RELAXED, __HIP_MEMORY_SCOPE_AGENT); }
; __device__ __forceinline__ unsigned xb_add(unsigned* p, unsigned v) { return __hip_atomic_fetch_add(p, v, __ATOMIC_RELAXED, __HIP_MEMORY_SCOPE_AGENT); }
; #define XB_SPIN(cond, bar) do { unsigned _sp = 0; while (cond) { __builtin_amdgcn_s_sleep(1); \
;     if ((++_sp & 255u) == 0u) { if (xb_ld(&(bar)[XB_TMO])) break; if (_sp > XB_SPIN_CAP) { atomicAdd(&(bar)[XB_TMO], 1u); break; } } } } while (0)
; __device__ __forceinline__ void xcd_barrier(const XcdBarrier& b) {
;     ...
;         if (old + 1u == (gen + 1u) * nloc) {
;             __builtin_amdgcn_fence(__ATOMIC_RELEASE, "agent");
;             asm volatile("s_waitcnt vmcnt(0)" ::: "memory");
;             const unsigned og = xb_add(&bar[XB_TOP], 1u);
;             const unsigned tg = og / nx;
;             if (og + 1u == (tg + 1u) * nx) xb_add(&bar[XB_TOPGEN], 1u);
;             else XB_SPIN(xb_ld(&bar[XB_TOPGEN]) == tg, bar);
;             __builtin_amdgcn_fence(__ATOMIC_ACQUIRE, "agent");
;             xb_add(&bar[XB_XGEN(b.x)], 1u);
.LBB0_923:
	s_or_b64 exec, exec, s[6:7]
	s_waitcnt vmcnt(0)
	v_readfirstlane_b32 s4, v5
	v_sub_u32_e32 v6, 0, v4
	s_mov_b64 s[8:9], -1
	v_add_u32_e32 v5, s4, v2
	v_cvt_f32_u32_e32 v2, v4
	s_add_u32 s4, s2, 0x83500
	s_addc_u32 s5, s3, 0
	v_rcp_iflag_f32_e32 v2, v2
	s_nop 0
	v_mul_f32_e32 v2, 0x4f7ffffe, v2
	v_cvt_u32_f32_e32 v2, v2
	v_mul_lo_u32 v6, v6, v2
	v_mul_hi_u32 v6, v2, v6
	v_add_u32_e32 v2, v2, v6
	v_mul_hi_u32 v2, v5, v2
	v_mul_lo_u32 v6, v2, v4
	v_sub_u32_e32 v6, v5, v6
	v_cmp_ge_u32_e32 vcc, v6, v4
	v_add_u32_e32 v7, 1, v2
	v_add_u32_e32 v5, 1, v5
	v_cndmask_b32_e32 v2, v2, v7, vcc
	v_sub_u32_e32 v7, v6, v4
	v_cndmask_b32_e32 v6, v6, v7, vcc
	v_cmp_ge_u32_e32 vcc, v6, v4
	v_add_u32_e32 v6, 1, v2
	s_nop 0
	v_cndmask_b32_e32 v2, v2, v6, vcc
	v_mul_lo_u32 v6, v4, v2
	v_add_u32_e32 v4, v6, v4
	v_cmp_ne_u32_e32 vcc, v5, v4
	v_mov_b64_e32 v[4:5], s[4:5]
	s_and_saveexec_b64 s[6:7], vcc
	s_cbranch_execz .LBB0_935
	global_load_dword v4, v3, s[100:101] sc1
	s_mov_b64 s[16:17], 0
	s_waitcnt vmcnt(0)
	v_cmp_lt_u32_e32 vcc, v4, v19
	s_and_saveexec_b64 s[14:15], vcc
	s_cbranch_execz .LBB0_934
	s_add_u32 s8, s2, 0x80200
	s_addc_u32 s9, s3, 0
	s_mov_b32 s41, 1
	s_mov_b64 s[2:3], 0
	s_branch .LBB0_927

; __device__ __forceinline__ unsigned xb_ld(unsigned* p)              { return __hip_atomic_load(p, __ATOMIC_RELAXED, __HIP_MEMORY_SCOPE_AGENT); }
; __device__ __forceinline__ unsigned xb_add(unsigned* p, unsigned v) { return __hip_atomic_fetch_add(p, v, __ATOMIC_RELAXED, __HIP_MEMORY_SCOPE_AGENT); }
; #define XB_SPIN(cond, bar) do { unsigned _sp = 0; while (cond) { __builtin_amdgcn_s_sleep(1); \
;     if ((++_sp & 255u) == 0u) { if (xb_ld(&(bar)[XB_TMO])) break; if (_sp > XB_SPIN_CAP) { atomicAdd(&(bar)[XB_TMO], 1u); break; } } } } while (0)
; __device__ __forceinline__ void xcd_barrier(const XcdBarrier& b) {
;     ...
;         const unsigned old = xb_add(&bar[XB_XSUB(b.x)], 1u);
;         const unsigned gen = old / nloc;
;         if (old + 1u == (gen + 1u) * nloc) {
;             __builtin_amdgcn_fence(__ATOMIC_RELEASE, "agent");
;             asm volatile("s_waitcnt vmcnt(0)" ::: "memory");
;             const unsigned og = xb_add(&bar[XB_TOP], 1u);
;             const unsigned tg = og / nx;
;             if (og + 1u == (tg + 1u) * nx) xb_add(&bar[XB_TOPGEN], 1u);
;             else XB_SPIN(xb_ld(&bar[XB_TOPGEN]) == tg, bar);
;             __builtin_amdgcn_fence(__ATOMIC_ACQUIRE, "agent");
;             xb_add(&bar[XB_XGEN(b.x)], 1u);
;             asm volatile("s_waitcnt vmcnt(0)" ::: "memory");
;         } else {
;             XB_SPIN(xb_ld(&bar[XB_XGEN(b.x)]) == gen, bar);
;             __builtin_amdgcn_fence(__ATOMIC_ACQUIRE, "agent");
;             asm volatile("s_waitcnt vmcnt(0)" ::: "memory");
.LBB0_1099:
	s_or_b64 exec, exec, s[6:7]
	v_cvt_f32_u32_e32 v7, v5
	s_waitcnt vmcnt(0)
	v_readfirstlane_b32 s4, v6
	v_sub_u32_e32 v6, 0, v5
	v_rcp_iflag_f32_e32 v7, v7
	v_add_u32_e32 v8, s4, v2
	v_mul_f32_e32 v7, 0x4f7ffffe, v7
	v_cvt_u32_f32_e32 v7, v7
	v_mul_lo_u32 v2, v6, v7
	v_mul_hi_u32 v2, v7, v2
	v_add_u32_e32 v2, v7, v2
	v_mul_hi_u32 v2, v8, v2
	v_mul_lo_u32 v6, v2, v5
	v_sub_u32_e32 v6, v8, v6
	v_add_u32_e32 v7, 1, v2
	v_cmp_ge_u32_e32 vcc, v6, v5
	s_nop 1
	v_cndmask_b32_e32 v2, v2, v7, vcc
	v_sub_u32_e32 v7, v6, v5
	v_cndmask_b32_e32 v6, v6, v7, vcc
	v_add_u32_e32 v7, 1, v2
	v_cmp_ge_u32_e32 vcc, v6, v5
	v_add_u32_e32 v6, 1, v8
	s_nop 0
	v_cndmask_b32_e32 v2, v2, v7, vcc
	v_mul_lo_u32 v7, v5, v2
	v_add_u32_e32 v5, v7, v5
	v_cmp_ne_u32_e32 vcc, v6, v5
	s_waitcnt lgkmcnt(0)
	v_mad_u32_u24 v19, v2, v4, v4
	s_add_u32 s100, s2, 0x83400
	s_addc_u32 s101, s3, 0
	s_and_saveexec_b64 s[4:5], vcc
	s_xor_b64 s[4:5], exec, s[4:5]
	s_cbranch_execz .LBB0_1113
	s_add_i32 s6, s40, 0x900
	s_mov_b32 s7, s31
	s_lshl_b64 s[6:7], s[6:7], 2
	s_add_u32 s46, s34, s6
	s_addc_u32 s47, s35, s7
	s_waitcnt lgkmcnt(0)
	global_load_dword v4, v3, s[100:101] sc1
	s_waitcnt vmcnt(0)
	v_cmp_lt_u32_e32 vcc, v4, v19
	s_and_saveexec_b64 s[6:7], vcc
	s_cbranch_execz .LBB0_1112
	s_add_u32 s14, s2, 0x80200
	s_addc_u32 s15, s3, 0
	s_mov_b32 s41, 1
	s_mov_b64 s[52:53], 0
	s_branch .LBB0_1103

; __device__ __forceinline__ unsigned xb_ld(unsigned* p)              { return __hip_atomic_load(p, __ATOMIC_RELAXED, __HIP_MEMORY_SCOPE_AGENT); }
; __device__ __forceinline__ unsigned xb_add(unsigned* p, unsigned v) { return __hip_atomic_fetch_add(p, v, __ATOMIC_RELAXED, __HIP_MEMORY_SCOPE_AGENT); }
; #define XB_SPIN(cond, bar) do { unsigned _sp = 0; while (cond) { __builtin_amdgcn_s_sleep(1); \
;     if ((++_sp & 255u) == 0u) { if (xb_ld(&(bar)[XB_TMO])) break; if (_sp > XB_SPIN_CAP) { atomicAdd(&(bar)[XB_TMO], 1u); break; } } } } while (0)
; __device__ __forceinline__ void xcd_barrier(const XcdBarrier& b) {
;     ...
;         if (old + 1u == (gen + 1u) * nloc) {
;             __builtin_amdgcn_fence(__ATOMIC_RELEASE, "agent");
;             asm volatile("s_waitcnt vmcnt(0)" ::: "memory");
;             const unsigned og = xb_add(&bar[XB_TOP], 1u);
;             const unsigned tg = og / nx;
;             if (og + 1u == (tg + 1u) * nx) xb_add(&bar[XB_TOPGEN], 1u);
;             else XB_SPIN(xb_ld(&bar[XB_TOPGEN]) == tg, bar);
;             __builtin_amdgcn_fence(__ATOMIC_ACQUIRE, "agent");
;             xb_add(&bar[XB_XGEN(b.x)], 1u);
.LBB0_1116:
	s_or_b64 exec, exec, s[6:7]
	s_waitcnt vmcnt(0)
	v_readfirstlane_b32 s4, v5
	v_sub_u32_e32 v6, 0, v4
	s_mov_b64 s[14:15], -1
	v_add_u32_e32 v5, s4, v2
	v_cvt_f32_u32_e32 v2, v4
	s_add_u32 s4, s2, 0x83500
	s_addc_u32 s5, s3, 0
	v_rcp_iflag_f32_e32 v2, v2
	s_nop 0
	v_mul_f32_e32 v2, 0x4f7ffffe, v2
	v_cvt_u32_f32_e32 v2, v2
	v_mul_lo_u32 v6, v6, v2
	v_mul_hi_u32 v6, v2, v6
	v_add_u32_e32 v2, v2, v6
	v_mul_hi_u32 v2, v5, v2
	v_mul_lo_u32 v6, v2, v4
	v_sub_u32_e32 v6, v5, v6
	v_cmp_ge_u32_e32 vcc, v6, v4
	v_add_u32_e32 v7, 1, v2
	v_add_u32_e32 v5, 1, v5
	v_cndmask_b32_e32 v2, v2, v7, vcc
	v_sub_u32_e32 v7, v6, v4
	v_cndmask_b32_e32 v6, v6, v7, vcc
	v_cmp_ge_u32_e32 vcc, v6, v4
	v_add_u32_e32 v6, 1, v2
	s_nop 0
	v_cndmask_b32_e32 v2, v2, v6, vcc
	v_mul_lo_u32 v6, v4, v2
	v_add_u32_e32 v4, v6, v4
	v_cmp_ne_u32_e32 vcc, v5, v4
	v_mov_b64_e32 v[4:5], s[4:5]
	s_and_saveexec_b64 s[6:7], vcc
	s_cbranch_execz .LBB0_1128
	global_load_dword v4, v3, s[100:101] sc1
	s_mov_b64 s[16:17], 0
	s_waitcnt vmcnt(0)
	v_cmp_lt_u32_e32 vcc, v4, v19
	s_and_saveexec_b64 s[46:47], vcc
	s_cbranch_execz .LBB0_1127
	s_add_u32 s14, s2, 0x80200
	s_addc_u32 s15, s3, 0
	s_mov_b32 s41, 1
	s_mov_b64 s[2:3], 0
	s_branch .LBB0_1120

; __device__ __forceinline__ unsigned xb_ld(unsigned* p)              { return __hip_atomic_load(p, __ATOMIC_RELAXED, __HIP_MEMORY_SCOPE_AGENT); }
; __device__ __forceinline__ unsigned xb_add(unsigned* p, unsigned v) { return __hip_atomic_fetch_add(p, v, __ATOMIC_RELAXED, __HIP_MEMORY_SCOPE_AGENT); }
; #define XB_SPIN(cond, bar) do { unsigned _sp = 0; while (cond) { __builtin_amdgcn_s_sleep(1); \
;     if ((++_sp & 255u) == 0u) { if (xb_ld(&(bar)[XB_TMO])) break; if (_sp > XB_SPIN_CAP) { atomicAdd(&(bar)[XB_TMO], 1u); break; } } } } while (0)
; __device__ __forceinline__ void xcd_barrier(const XcdBarrier& b) {
;     ...
;         const unsigned old = xb_add(&bar[XB_XSUB(b.x)], 1u);
;         const unsigned gen = old / nloc;
;         if (old + 1u == (gen + 1u) * nloc) {
;             __builtin_amdgcn_fence(__ATOMIC_RELEASE, "agent");
;             asm volatile("s_waitcnt vmcnt(0)" ::: "memory");
;             const unsigned og = xb_add(&bar[XB_TOP], 1u);
;             const unsigned tg = og / nx;
;             if (og + 1u == (tg + 1u) * nx) xb_add(&bar[XB_TOPGEN], 1u);
;             else XB_SPIN(xb_ld(&bar[XB_TOPGEN]) == tg, bar);
;             __builtin_amdgcn_fence(__ATOMIC_ACQUIRE, "agent");
;             xb_add(&bar[XB_XGEN(b.x)], 1u);
;             asm volatile("s_waitcnt vmcnt(0)" ::: "memory");
;         } else {
;             XB_SPIN(xb_ld(&bar[XB_XGEN(b.x)]) == gen, bar);
;             __builtin_amdgcn_fence(__ATOMIC_ACQUIRE, "agent");
;             asm volatile("s_waitcnt vmcnt(0)" ::: "memory");
.LBB0_1167:
	s_or_b64 exec, exec, s[14:15]
	v_cvt_f32_u32_e32 v7, v5
	s_waitcnt vmcnt(0)
	v_readfirstlane_b32 s6, v6
	v_sub_u32_e32 v6, 0, v5
	v_rcp_iflag_f32_e32 v7, v7
	v_add_u32_e32 v8, s6, v2
	v_mul_f32_e32 v7, 0x4f7ffffe, v7
	v_cvt_u32_f32_e32 v7, v7
	v_mul_lo_u32 v2, v6, v7
	v_mul_hi_u32 v2, v7, v2
	v_add_u32_e32 v2, v7, v2
	v_mul_hi_u32 v2, v8, v2
	v_mul_lo_u32 v6, v2, v5
	v_sub_u32_e32 v6, v8, v6
	v_add_u32_e32 v7, 1, v2
	v_cmp_ge_u32_e32 vcc, v6, v5
	s_nop 1
	v_cndmask_b32_e32 v2, v2, v7, vcc
	v_sub_u32_e32 v7, v6, v5
	v_cndmask_b32_e32 v6, v6, v7, vcc
	v_add_u32_e32 v7, 1, v2
	v_cmp_ge_u32_e32 vcc, v6, v5
	v_add_u32_e32 v6, 1, v8
	s_nop 0
	v_cndmask_b32_e32 v2, v2, v7, vcc
	v_mul_lo_u32 v7, v5, v2
	v_add_u32_e32 v5, v7, v5
	v_cmp_ne_u32_e32 vcc, v6, v5
	s_waitcnt lgkmcnt(0)
	v_mad_u32_u24 v19, v2, v4, v4
	s_add_u32 s100, s4, 0x83400
	s_addc_u32 s101, s5, 0
	s_and_saveexec_b64 s[6:7], vcc
	s_xor_b64 s[6:7], exec, s[6:7]
	s_cbranch_execz .LBB0_1181
	s_add_i32 s10, s40, 0x900
	s_mov_b32 s11, s31
	s_lshl_b64 s[10:11], s[10:11], 2
	s_add_u32 s52, s34, s10
	s_addc_u32 s53, s35, s11
	s_waitcnt lgkmcnt(0)
	global_load_dword v4, v3, s[100:101] sc1
	s_waitcnt vmcnt(0)
	v_cmp_lt_u32_e32 vcc, v4, v19
	s_and_saveexec_b64 s[14:15], vcc
	s_cbranch_execz .LBB0_1180
	s_add_u32 s46, s4, 0x80200
	s_addc_u32 s47, s5, 0
	s_mov_b32 s41, 1
	s_mov_b64 s[58:59], 0
	s_branch .LBB0_1171

; __device__ __forceinline__ unsigned xb_ld(unsigned* p)              { return __hip_atomic_load(p, __ATOMIC_RELAXED, __HIP_MEMORY_SCOPE_AGENT); }
; __device__ __forceinline__ unsigned xb_add(unsigned* p, unsigned v) { return __hip_atomic_fetch_add(p, v, __ATOMIC_RELAXED, __HIP_MEMORY_SCOPE_AGENT); }
; #define XB_SPIN(cond, bar) do { unsigned _sp = 0; while (cond) { __builtin_amdgcn_s_sleep(1); \
;     if ((++_sp & 255u) == 0u) { if (xb_ld(&(bar)[XB_TMO])) break; if (_sp > XB_SPIN_CAP) { atomicAdd(&(bar)[XB_TMO], 1u); break; } } } } while (0)
; __device__ __forceinline__ void xcd_barrier(const XcdBarrier& b) {
;     ...
;         if (old + 1u == (gen + 1u) * nloc) {
;             __builtin_amdgcn_fence(__ATOMIC_RELEASE, "agent");
;             asm volatile("s_waitcnt vmcnt(0)" ::: "memory");
;             const unsigned og = xb_add(&bar[XB_TOP], 1u);
;             const unsigned tg = og / nx;
;             if (og + 1u == (tg + 1u) * nx) xb_add(&bar[XB_TOPGEN], 1u);
;             else XB_SPIN(xb_ld(&bar[XB_TOPGEN]) == tg, bar);
;             __builtin_amdgcn_fence(__ATOMIC_ACQUIRE, "agent");
;             xb_add(&bar[XB_XGEN(b.x)], 1u);
.LBB0_1184:
	s_or_b64 exec, exec, s[14:15]
	s_waitcnt vmcnt(0)
	v_readfirstlane_b32 s6, v5
	v_sub_u32_e32 v6, 0, v4
	s_mov_b64 s[16:17], -1
	v_add_u32_e32 v5, s6, v2
	v_cvt_f32_u32_e32 v2, v4
	s_add_u32 s6, s4, 0x83500
	s_addc_u32 s7, s5, 0
	v_rcp_iflag_f32_e32 v2, v2
	s_nop 0
	v_mul_f32_e32 v2, 0x4f7ffffe, v2
	v_cvt_u32_f32_e32 v2, v2
	v_mul_lo_u32 v6, v6, v2
	v_mul_hi_u32 v6, v2, v6
	v_add_u32_e32 v2, v2, v6
	v_mul_hi_u32 v2, v5, v2
	v_mul_lo_u32 v6, v2, v4
	v_sub_u32_e32 v6, v5, v6
	v_cmp_ge_u32_e32 vcc, v6, v4
	v_add_u32_e32 v7, 1, v2
	v_add_u32_e32 v5, 1, v5
	v_cndmask_b32_e32 v2, v2, v7, vcc
	v_sub_u32_e32 v7, v6, v4
	v_cndmask_b32_e32 v6, v6, v7, vcc
	v_cmp_ge_u32_e32 vcc, v6, v4
	v_add_u32_e32 v6, 1, v2
	s_nop 0
	v_cndmask_b32_e32 v2, v2, v6, vcc
	v_mul_lo_u32 v6, v4, v2
	v_add_u32_e32 v4, v6, v4
	v_cmp_ne_u32_e32 vcc, v5, v4
	v_mov_b64_e32 v[4:5], s[6:7]
	s_and_saveexec_b64 s[14:15], vcc
	s_cbranch_execz .LBB0_1196
	global_load_dword v4, v3, s[100:101] sc1
	s_mov_b64 s[16:17], 0
	s_waitcnt vmcnt(0)
	v_cmp_lt_u32_e32 vcc, v4, v19
	s_and_saveexec_b64 s[52:53], vcc
	s_cbranch_execz .LBB0_1195
	s_add_u32 s46, s4, 0x80200
	s_addc_u32 s47, s5, 0
	s_mov_b32 s41, 1
	s_mov_b64 s[4:5], 0
	s_branch .LBB0_1188

; __device__ __forceinline__ unsigned xb_ld(unsigned* p)              { return __hip_atomic_load(p, __ATOMIC_RELAXED, __HIP_MEMORY_SCOPE_AGENT); }
; __device__ __forceinline__ unsigned xb_add(unsigned* p, unsigned v) { return __hip_atomic_fetch_add(p, v, __ATOMIC_RELAXED, __HIP_MEMORY_SCOPE_AGENT); }
; #define XB_SPIN(cond, bar) do { unsigned _sp = 0; while (cond) { __builtin_amdgcn_s_sleep(1); \
;     if ((++_sp & 255u) == 0u) { if (xb_ld(&(bar)[XB_TMO])) break; if (_sp > XB_SPIN_CAP) { atomicAdd(&(bar)[XB_TMO], 1u); break; } } } } while (0)
; __device__ __forceinline__ void xcd_barrier(const XcdBarrier& b) {
;     ...
;         const unsigned old = xb_add(&bar[XB_XSUB(b.x)], 1u);
;         const unsigned gen = old / nloc;
;         if (old + 1u == (gen + 1u) * nloc) {
;             __builtin_amdgcn_fence(__ATOMIC_RELEASE, "agent");
;             asm volatile("s_waitcnt vmcnt(0)" ::: "memory");
;             const unsigned og = xb_add(&bar[XB_TOP], 1u);
;             const unsigned tg = og / nx;
;             if (og + 1u == (tg + 1u) * nx) xb_add(&bar[XB_TOPGEN], 1u);
;             else XB_SPIN(xb_ld(&bar[XB_TOPGEN]) == tg, bar);
;             __builtin_amdgcn_fence(__ATOMIC_ACQUIRE, "agent");
;             xb_add(&bar[XB_XGEN(b.x)], 1u);
;             asm volatile("s_waitcnt vmcnt(0)" ::: "memory");
;         } else {
;             XB_SPIN(xb_ld(&bar[XB_XGEN(b.x)]) == gen, bar);
;             __builtin_amdgcn_fence(__ATOMIC_ACQUIRE, "agent");
;             asm volatile("s_waitcnt vmcnt(0)" ::: "memory");
.LBB0_1261:
	s_or_b64 exec, exec, s[6:7]
	v_cvt_f32_u32_e32 v7, v5
	s_waitcnt vmcnt(0)
	v_readfirstlane_b32 s4, v6
	v_sub_u32_e32 v6, 0, v5
	v_rcp_iflag_f32_e32 v7, v7
	v_add_u32_e32 v8, s4, v2
	v_mul_f32_e32 v7, 0x4f7ffffe, v7
	v_cvt_u32_f32_e32 v7, v7
	v_mul_lo_u32 v2, v6, v7
	v_mul_hi_u32 v2, v7, v2
	v_add_u32_e32 v2, v7, v2
	v_mul_hi_u32 v2, v8, v2
	v_mul_lo_u32 v6, v2, v5
	v_sub_u32_e32 v6, v8, v6
	v_add_u32_e32 v7, 1, v2
	v_cmp_ge_u32_e32 vcc, v6, v5
	s_nop 1
	v_cndmask_b32_e32 v2, v2, v7, vcc
	v_sub_u32_e32 v7, v6, v5
	v_cndmask_b32_e32 v6, v6, v7, vcc
	v_add_u32_e32 v7, 1, v2
	v_cmp_ge_u32_e32 vcc, v6, v5
	v_add_u32_e32 v6, 1, v8
	s_nop 0
	v_cndmask_b32_e32 v2, v2, v7, vcc
	v_mul_lo_u32 v7, v5, v2
	v_add_u32_e32 v5, v7, v5
	v_cmp_ne_u32_e32 vcc, v6, v5
	s_waitcnt lgkmcnt(0)
	v_mad_u32_u24 v19, v2, v4, v4
	s_add_u32 s100, s2, 0x83400
	s_addc_u32 s101, s3, 0
	s_and_saveexec_b64 s[4:5], vcc
	s_xor_b64 s[4:5], exec, s[4:5]
	s_cbranch_execz .LBB0_1275
	s_add_i32 s30, s40, 0x900
	s_lshl_b64 s[6:7], s[30:31], 2
	s_add_u32 s46, s34, s6
	s_addc_u32 s47, s35, s7
	s_waitcnt lgkmcnt(0)
	global_load_dword v4, v3, s[100:101] sc1
	s_waitcnt vmcnt(0)
	v_cmp_lt_u32_e32 vcc, v4, v19
	s_and_saveexec_b64 s[6:7], vcc
	s_cbranch_execz .LBB0_1274
	s_add_u32 s14, s2, 0x80200
	s_addc_u32 s15, s3, 0
	s_mov_b32 s30, 1
	s_mov_b64 s[52:53], 0
	s_branch .LBB0_1265

; __device__ __forceinline__ unsigned xb_ld(unsigned* p)              { return __hip_atomic_load(p, __ATOMIC_RELAXED, __HIP_MEMORY_SCOPE_AGENT); }
; __device__ __forceinline__ unsigned xb_add(unsigned* p, unsigned v) { return __hip_atomic_fetch_add(p, v, __ATOMIC_RELAXED, __HIP_MEMORY_SCOPE_AGENT); }
; #define XB_SPIN(cond, bar) do { unsigned _sp = 0; while (cond) { __builtin_amdgcn_s_sleep(1); \
;     if ((++_sp & 255u) == 0u) { if (xb_ld(&(bar)[XB_TMO])) break; if (_sp > XB_SPIN_CAP) { atomicAdd(&(bar)[XB_TMO], 1u); break; } } } } while (0)
; __device__ __forceinline__ void xcd_barrier(const XcdBarrier& b) {
;     ...
;         if (old + 1u == (gen + 1u) * nloc) {
;             __builtin_amdgcn_fence(__ATOMIC_RELEASE, "agent");
;             asm volatile("s_waitcnt vmcnt(0)" ::: "memory");
;             const unsigned og = xb_add(&bar[XB_TOP], 1u);
;             const unsigned tg = og / nx;
;             if (og + 1u == (tg + 1u) * nx) xb_add(&bar[XB_TOPGEN], 1u);
;             else XB_SPIN(xb_ld(&bar[XB_TOPGEN]) == tg, bar);
;             __builtin_amdgcn_fence(__ATOMIC_ACQUIRE, "agent");
;             xb_add(&bar[XB_XGEN(b.x)], 1u);
.LBB0_1278:
	s_or_b64 exec, exec, s[6:7]
	s_waitcnt vmcnt(0)
	v_readfirstlane_b32 s4, v5
	v_sub_u32_e32 v6, 0, v4
	s_mov_b64 s[14:15], -1
	v_add_u32_e32 v5, s4, v2
	v_cvt_f32_u32_e32 v2, v4
	s_add_u32 s4, s2, 0x83500
	s_addc_u32 s5, s3, 0
	v_rcp_iflag_f32_e32 v2, v2
	s_nop 0
	v_mul_f32_e32 v2, 0x4f7ffffe, v2
	v_cvt_u32_f32_e32 v2, v2
	v_mul_lo_u32 v6, v6, v2
	v_mul_hi_u32 v6, v2, v6
	v_add_u32_e32 v2, v2, v6
	v_mul_hi_u32 v2, v5, v2
	v_mul_lo_u32 v6, v2, v4
	v_sub_u32_e32 v6, v5, v6
	v_cmp_ge_u32_e32 vcc, v6, v4
	v_add_u32_e32 v7, 1, v2
	v_add_u32_e32 v5, 1, v5
	v_cndmask_b32_e32 v2, v2, v7, vcc
	v_sub_u32_e32 v7, v6, v4
	v_cndmask_b32_e32 v6, v6, v7, vcc
	v_cmp_ge_u32_e32 vcc, v6, v4
	v_add_u32_e32 v6, 1, v2
	s_nop 0
	v_cndmask_b32_e32 v2, v2, v6, vcc
	v_mul_lo_u32 v6, v4, v2
	v_add_u32_e32 v4, v6, v4
	v_cmp_ne_u32_e32 vcc, v5, v4
	v_mov_b64_e32 v[4:5], s[4:5]
	s_and_saveexec_b64 s[6:7], vcc
	s_cbranch_execz .LBB0_1290
	global_load_dword v4, v3, s[100:101] sc1
	s_mov_b64 s[16:17], 0
	s_waitcnt vmcnt(0)
	v_cmp_lt_u32_e32 vcc, v4, v19
	s_and_saveexec_b64 s[46:47], vcc
	s_cbranch_execz .LBB0_1289
	s_add_u32 s14, s2, 0x80200
	s_addc_u32 s15, s3, 0
	s_mov_b32 s30, 1
	s_mov_b64 s[2:3], 0
	s_branch .LBB0_1282
